# nt on the P5 HGRN readout output stores (streamed producer output)
# baseline (speedup 1.0000x reference)
; __device__ __forceinline__ float bflo(unsigned u) { return __uint_as_float(u << 16); }
; __device__ __forceinline__ float bfhi(unsigned u) { return __uint_as_float(u & 0xffff0000u); }
; __device__ __forceinline__ float sigm(float x) { return __builtin_amdgcn_rcpf(1.0f + __expf(-x)); }
; __global__ void __launch_bounds__(512, 2) fwd_mega(Args args) {
;     ...
;         for (int m = gw; m < M; m += NGW) {
;             const size_t o = (size_t)m * 1024 + 16 * lane;
;             const u32x4 a0 = __builtin_nontemporal_load((const u32x4*)(OF + o)), a1 = __builtin_nontemporal_load((const u32x4*)(OF + o + 8)), b0 = __builtin_nontemporal_load((const u32x4*)(OB + o)), b1 = __builtin_nontemporal_load((const u32x4*)(OB + o + 8));
;             const u32x4 g0 = __builtin_nontemporal_load((const u32x4*)(U1 + (size_t)m * U1W + C_HOG + 16 * lane)), g1 = __builtin_nontemporal_load((const u32x4*)(U1 + (size_t)m * U1W + C_HOG + 16 * lane + 8));
;             float v[16], gg[16];
; #pragma unroll
;             for (int i = 0; i < 4; ++i) { v[2 * i] = pg8::bflo(a0[i]) + pg8::bflo(b0[i]); v[2 * i + 1] = pg8::bfhi(a0[i]) + pg8::bfhi(b0[i]);
;                 v[8 + 2 * i] = pg8::bflo(a1[i]) + pg8::bflo(b1[i]); v[8 + 2 * i + 1] = pg8::bfhi(a1[i]) + pg8::bfhi(b1[i]);
;                 gg[2 * i] = pg8::bflo(g0[i]); gg[2 * i + 1] = pg8::bfhi(g0[i]); gg[8 + 2 * i] = pg8::bflo(g1[i]); gg[8 + 2 * i + 1] = pg8::bfhi(g1[i]); }
;             float ss = 0.f;
; #pragma unroll
;             for (int i = 0; i < 16; ++i) ss += v[i] * v[i];
;             ss += __shfl_xor(ss, 1); ss += __shfl_xor(ss, 2); ss += __shfl_xor(ss, 4);
;             const float rstd = 1.0f / sqrtf(ss * (1.0f / 128.0f) + EPS);
;             const float* gp = hg_g + 16 * (lane & 7);
;             float y[16];
; #pragma unroll
;             for (int i = 0; i < 16; ++i) y[i] = v[i] * rstd * gp[i] * (gg[i] * pg8::sigm(gg[i]));
.LBB0_728:
	v_lshl_add_u64 v[22:23], s[24:25], 0, v[20:21]
	v_add_co_u32_e32 v38, vcc, 0xc000000, v22
	v_lshl_add_u64 v[24:25], s[28:29], 0, v[20:21]
	s_nop 0
	v_addc_co_u32_e32 v39, vcc, 0, v23, vcc
	v_lshl_add_u64 v[42:43], v[24:25], 0, s[34:35]
	v_add_co_u32_e32 v24, vcc, s3, v24
	v_lshl_add_u64 v[26:27], s[8:9], 0, v[20:21]
	s_nop 0
	v_addc_co_u32_e32 v25, vcc, 0, v25, vcc
	v_lshl_add_u64 v[34:35], v[22:23], 0, s[30:31]
	s_waitcnt vmcnt(0)
	v_add_co_u32_e32 v52, vcc, s6, v26
	global_load_dwordx4 v[2:5], v[18:19], off offset:48
	global_load_dwordx4 v[6:9], v[18:19], off offset:32
	global_load_dwordx4 v[10:13], v[18:19], off offset:16
	global_load_dwordx4 v[14:17], v[18:19], off
	v_lshl_add_u64 v[50:51], v[26:27], 0, s[36:37]
	global_load_dwordx4 v[34:37], v[34:35], off offset:16 nt
	s_nop 0
	global_load_dwordx4 v[38:41], v[38:39], off nt
	s_nop 0
	global_load_dwordx4 v[42:45], v[42:43], off offset:16 nt
	s_nop 0
	global_load_dwordx4 v[46:49], v[24:25], off nt
	v_addc_co_u32_e32 v53, vcc, 0, v27, vcc
	global_load_dwordx4 v[24:27], v[50:51], off offset:16 nt
	s_nop 0
	global_load_dwordx4 v[50:53], v[52:53], off offset:2048 nt
	s_add_i32 s16, s16, s18
	s_add_u32 s8, s8, s22
	s_addc_u32 s9, s9, s23
	s_add_u32 s24, s24, s26
	s_addc_u32 s25, s25, s27
	s_add_u32 s28, s28, s26
	s_addc_u32 s29, s29, s27
	s_cmp_lt_i32 s16, 0x8000
	s_waitcnt vmcnt(9)
	v_mov_b32_e32 v55, v5
	s_waitcnt vmcnt(5)
	v_lshlrev_b32_e32 v56, 16, v37
	v_and_b32_e32 v57, 0xffff0000, v37
	v_lshlrev_b32_e32 v58, 16, v36
	v_and_b32_e32 v59, 0xffff0000, v36
	v_lshlrev_b32_e32 v36, 16, v35
	v_and_b32_e32 v37, 0xffff0000, v35
	v_lshlrev_b32_e32 v60, 16, v34
	v_and_b32_e32 v61, 0xffff0000, v34
	s_waitcnt vmcnt(4)
	v_lshlrev_b32_e32 v34, 16, v41
	v_and_b32_e32 v35, 0xffff0000, v41
	v_lshlrev_b32_e32 v62, 16, v40
	v_and_b32_e32 v63, 0xffff0000, v40
	v_lshlrev_b32_e32 v40, 16, v39
	v_and_b32_e32 v41, 0xffff0000, v39
	v_lshlrev_b32_e32 v64, 16, v38
	v_and_b32_e32 v65, 0xffff0000, v38
	s_waitcnt vmcnt(3)
	v_lshlrev_b32_e32 v38, 16, v45
	v_and_b32_e32 v39, 0xffff0000, v45
	v_lshlrev_b32_e32 v66, 16, v44
	v_and_b32_e32 v67, 0xffff0000, v44
	v_lshlrev_b32_e32 v44, 16, v43
	v_and_b32_e32 v45, 0xffff0000, v43
	v_lshlrev_b32_e32 v68, 16, v42
	v_and_b32_e32 v69, 0xffff0000, v42
	s_waitcnt vmcnt(2)
	v_lshlrev_b32_e32 v42, 16, v49
	v_and_b32_e32 v43, 0xffff0000, v49
	v_lshlrev_b32_e32 v70, 16, v48
	v_and_b32_e32 v71, 0xffff0000, v48
	v_lshlrev_b32_e32 v48, 16, v47
	v_and_b32_e32 v49, 0xffff0000, v47
	v_lshlrev_b32_e32 v72, 16, v46
	v_and_b32_e32 v73, 0xffff0000, v46
	s_waitcnt vmcnt(1)
	v_lshlrev_b32_e32 v5, 16, v27
	v_and_b32_e32 v54, 0xffff0000, v27
	v_pk_add_f32 v[38:39], v[56:57], v[38:39]
	v_pk_add_f32 v[46:47], v[58:59], v[66:67]
	v_lshlrev_b32_e32 v56, 16, v26
	v_and_b32_e32 v57, 0xffff0000, v26
	v_pk_add_f32 v[26:27], v[36:37], v[44:45]
	v_lshlrev_b32_e32 v36, 16, v25
	v_and_b32_e32 v37, 0xffff0000, v25
	v_pk_add_f32 v[44:45], v[60:61], v[68:69]
	v_lshlrev_b32_e32 v58, 16, v24
	v_and_b32_e32 v59, 0xffff0000, v24
	v_pk_add_f32 v[24:25], v[34:35], v[42:43]
	s_waitcnt vmcnt(0)
	v_lshlrev_b32_e32 v34, 16, v53
	v_and_b32_e32 v35, 0xffff0000, v53
	v_lshlrev_b32_e32 v60, 16, v52
	v_and_b32_e32 v61, 0xffff0000, v52
	v_pk_add_f32 v[40:41], v[40:41], v[48:49]
	v_and_b32_e32 v49, 0xffff0000, v51
	v_pk_add_f32 v[52:53], v[64:65], v[72:73]
	v_pk_add_f32 v[42:43], v[62:63], v[70:71]
	v_lshlrev_b32_e32 v48, 16, v51
	v_and_b32_e32 v63, 0xffff0000, v50
	v_mul_f32_e32 v33, 0xbfb8aa3b, v36
	v_mul_f32_e32 v80, 0xbfb8aa3b, v59
	v_mul_f32_e32 v83, 0xbfb8aa3b, v60
	v_mul_f32_e32 v86, 0xbfb8aa3b, v49
	v_pk_mul_f32 v[76:77], v[52:53], v[52:53]
	v_mul_f32_e32 v79, 0xbfb8aa3b, v58
	v_mul_f32_e32 v82, 0xbfb8aa3b, v35
	v_pk_mul_f32 v[74:75], v[40:41], v[40:41]
	v_mul_f32_e32 v85, 0xbfb8aa3b, v48
	v_mul_f32_e32 v88, 0xbfb8aa3b, v63
	v_mul_f32_e32 v89, 0xbfb8aa3b, v56
	v_mul_f32_e32 v90, 0xbfb8aa3b, v57
	v_mul_f32_e32 v91, 0xbfb8aa3b, v5
	v_exp_f32_e32 v33, v33
	v_exp_f32_e32 v80, v80
	v_exp_f32_e32 v83, v83
	v_exp_f32_e32 v86, v86
	v_add_f32_e32 v76, v76, v77
	v_exp_f32_e32 v79, v79
	v_exp_f32_e32 v82, v82
	v_exp_f32_e32 v85, v85
	v_exp_f32_e32 v88, v88
	v_exp_f32_e32 v77, v89
	v_exp_f32_e32 v89, v90
	v_exp_f32_e32 v90, v91
	v_add_f32_e32 v74, v76, v74
	v_pk_mul_f32 v[72:73], v[42:43], v[42:43]
	v_add_f32_e32 v74, v74, v75
	v_add_f32_e32 v72, v74, v72
	v_pk_mul_f32 v[70:71], v[24:25], v[24:25]
	v_add_f32_e32 v33, 1.0, v33
	v_add_f32_e32 v76, 1.0, v80
	v_add_f32_e32 v80, 1.0, v83
	v_add_f32_e32 v83, 1.0, v86
	v_add_f32_e32 v86, v72, v73
	v_add_f32_e32 v75, 1.0, v79
	v_add_f32_e32 v79, 1.0, v82
	v_add_f32_e32 v82, 1.0, v85
	v_add_f32_e32 v85, 1.0, v88
	v_add_f32_e32 v88, 1.0, v89
	v_add_f32_e32 v89, 1.0, v90
	v_rcp_f32_e32 v72, v33
	v_add_f32_e32 v33, v86, v70
	v_pk_mul_f32 v[68:69], v[44:45], v[44:45]
	v_rcp_f32_e32 v86, v89
	v_add_f32_e32 v33, v33, v71
	v_add_f32_e32 v33, v33, v68
	v_pk_mul_f32 v[66:67], v[26:27], v[26:27]
	v_add_f32_e32 v33, v33, v69
	v_add_f32_e32 v33, v33, v66
	v_pk_mul_f32 v[64:65], v[46:47], v[46:47]
	v_mul_f32_e32 v66, v86, v5
	v_add_f32_e32 v5, v33, v67
	v_add_f32_e32 v5, v5, v64
	v_lshlrev_b32_e32 v62, 16, v50
	v_pk_mul_f32 v[50:51], v[38:39], v[38:39]
	v_add_f32_e32 v5, v5, v65
	v_add_f32_e32 v5, v5, v50
	v_add_f32_e32 v5, v5, v51
	ds_bpermute_b32 v33, v28, v5
	v_mul_f32_e32 v78, 0xbfb8aa3b, v37
	v_mul_f32_e32 v81, 0xbfb8aa3b, v34
	v_mul_f32_e32 v84, 0xbfb8aa3b, v61
	v_mul_f32_e32 v87, 0xbfb8aa3b, v62
	s_waitcnt lgkmcnt(0)
; __device__ __forceinline__ float sigm(float x) { return __builtin_amdgcn_rcpf(1.0f + __expf(-x)); }
; DI unsigned pk2(float lo, float hi) { f32x2_t v = {lo, hi}; bf16x2_t b = __builtin_convertvector(v, bf16x2_t); return __builtin_bit_cast(unsigned, b); }
; __global__ void __launch_bounds__(512, 2) fwd_mega(Args args) {
;     ...
;             ss += __shfl_xor(ss, 1); ss += __shfl_xor(ss, 2); ss += __shfl_xor(ss, 4);
;             const float rstd = 1.0f / sqrtf(ss * (1.0f / 128.0f) + EPS);
;             const float* gp = hg_g + 16 * (lane & 7);
;             float y[16];
; #pragma unroll
;             for (int i = 0; i < 16; ++i) y[i] = v[i] * rstd * gp[i] * (gg[i] * pg8::sigm(gg[i]));
;             u32x4 w0, w1; w0.x = pk2(y[0], y[1]); w0.y = pk2(y[2], y[3]); w0.z = pk2(y[4], y[5]); w0.w = pk2(y[6], y[7]);
;             w1.x = pk2(y[8], y[9]); w1.y = pk2(y[10], y[11]); w1.z = pk2(y[12], y[13]); w1.w = pk2(y[14], y[15]);
;             *(u32x4*)(OHG + o) = w0; *(u32x4*)(OHG + o + 8) = w1;
	v_add_f32_e32 v5, v5, v33
	ds_bpermute_b32 v33, v29, v5
	v_mul_f32_e32 v92, 0xbfb8aa3b, v54
	v_exp_f32_e32 v78, v78
	v_exp_f32_e32 v81, v81
	v_exp_f32_e32 v84, v84
	s_waitcnt lgkmcnt(0)
	v_add_f32_e32 v5, v5, v33
	ds_bpermute_b32 v33, v30, v5
	v_exp_f32_e32 v87, v87
	v_exp_f32_e32 v91, v92
	v_add_f32_e32 v74, 1.0, v78
	v_add_f32_e32 v78, 1.0, v81
	s_waitcnt lgkmcnt(0)
	v_add_f32_e32 v5, v5, v33
	v_fmamk_f32 v5, v5, 0x3c000000, v31
	v_mul_f32_e32 v33, 0x4f800000, v5
	v_cmp_gt_f32_e32 vcc, s7, v5
	v_add_f32_e32 v81, 1.0, v84
	v_add_f32_e32 v84, 1.0, v87
	v_cndmask_b32_e32 v5, v5, v33, vcc
	v_sqrt_f32_e32 v33, v5
	v_add_f32_e32 v90, 1.0, v91
	v_add_f32_e32 v87, 1.0, v77
	v_rcp_f32_e32 v73, v74
	v_add_u32_e32 v50, -1, v33
	v_add_u32_e32 v51, 1, v33
	v_fma_f32 v64, -v50, v33, v5
	v_fma_f32 v65, -v51, v33, v5
	v_cmp_ge_f32_e64 s[0:1], 0, v64
	v_rcp_f32_e32 v74, v75
	v_rcp_f32_e32 v75, v76
	v_cndmask_b32_e64 v33, v33, v50, s[0:1]
	v_cmp_lt_f32_e64 s[0:1], 0, v65
	v_rcp_f32_e32 v76, v78
	v_rcp_f32_e32 v77, v79
	v_cndmask_b32_e64 v33, v33, v51, s[0:1]
	v_mul_f32_e32 v50, 0x37800000, v33
	v_cndmask_b32_e32 v33, v33, v50, vcc
	v_cmp_class_f32_e32 vcc, v5, v32
	v_rcp_f32_e32 v78, v80
	v_rcp_f32_e32 v79, v81
	v_cndmask_b32_e32 v5, v33, v5, vcc
	v_div_scale_f32 v33, s[0:1], v5, v5, 1.0
	v_rcp_f32_e32 v51, v33
	v_div_scale_f32 v50, vcc, 1.0, v5, 1.0
	v_rcp_f32_e32 v80, v82
	v_fma_f32 v64, -v33, v51, 1.0
	v_fmac_f32_e32 v51, v64, v51
	v_mul_f32_e32 v64, v50, v51
	v_fma_f32 v65, -v33, v64, v50
	v_fmac_f32_e32 v64, v65, v51
	v_rcp_f32_e32 v81, v83
	v_rcp_f32_e32 v82, v84
	v_rcp_f32_e32 v83, v85
	v_rcp_f32_e32 v70, v90
	v_fma_f32 v33, -v33, v64, v50
	v_rcp_f32_e32 v84, v87
	v_rcp_f32_e32 v85, v88
	v_div_fmas_f32 v33, v33, v51, v64
	v_div_fixup_f32 v50, v33, v5, 1.0
	v_pk_mul_f32 v[52:53], v[50:51], v[52:53] op_sel_hi:[0,1]
	v_pk_mul_f32 v[40:41], v[50:51], v[40:41] op_sel_hi:[0,1]
	v_pk_mul_f32 v[42:43], v[50:51], v[42:43] op_sel_hi:[0,1]
	v_pk_mul_f32 v[24:25], v[50:51], v[24:25] op_sel_hi:[0,1]
	v_mul_f32_e32 v5, v50, v38
	v_mul_f32_e32 v71, v50, v39
	v_pk_mul_f32 v[34:35], v[76:77], v[34:35]
	v_pk_mul_f32 v[60:61], v[78:79], v[60:61]
	v_pk_mul_f32 v[48:49], v[80:81], v[48:49]
	v_pk_mul_f32 v[62:63], v[82:83], v[62:63]
	v_pk_mul_f32 v[44:45], v[50:51], v[44:45] op_sel_hi:[0,1]
	v_pk_mul_f32 v[26:27], v[50:51], v[26:27] op_sel_hi:[0,1]
	v_pk_mul_f32 v[46:47], v[50:51], v[46:47] op_sel_hi:[0,1]
	v_pk_mul_f32 v[14:15], v[52:53], v[14:15]
	v_pk_mul_f32 v[16:17], v[40:41], v[16:17]
	v_pk_mul_f32 v[10:11], v[42:43], v[10:11]
	v_pk_mul_f32 v[12:13], v[24:25], v[12:13]
	v_mul_f32_e32 v24, v5, v4
	v_pk_mul_f32 v[4:5], v[70:71], v[54:55]
	v_pk_mul_f32 v[36:37], v[72:73], v[36:37]
	v_pk_mul_f32 v[58:59], v[74:75], v[58:59]
	v_pk_mul_f32 v[56:57], v[84:85], v[56:57]
	v_pk_mul_f32 v[6:7], v[44:45], v[6:7]
	v_pk_mul_f32 v[8:9], v[26:27], v[8:9]
	v_pk_mul_f32 v[2:3], v[46:47], v[2:3]
	v_pk_mul_f32 v[14:15], v[62:63], v[14:15]
	v_pk_mul_f32 v[16:17], v[48:49], v[16:17]
	v_pk_mul_f32 v[10:11], v[60:61], v[10:11]
	v_pk_mul_f32 v[12:13], v[34:35], v[12:13]
	v_mov_b32_e32 v67, v4
	v_mov_b32_e32 v25, v5
	v_pk_mul_f32 v[6:7], v[58:59], v[6:7]
	v_pk_mul_f32 v[8:9], v[36:37], v[8:9]
	v_pk_mul_f32 v[26:27], v[56:57], v[2:3]
	v_cvt_pk_bf16_f32 v2, v14, v15
	v_cvt_pk_bf16_f32 v3, v16, v17
	v_cvt_pk_bf16_f32 v4, v10, v11
	v_cvt_pk_bf16_f32 v5, v12, v13
	v_pk_mul_f32 v[10:11], v[66:67], v[24:25]
	v_cvt_pk_bf16_f32 v6, v6, v7
	v_cvt_pk_bf16_f32 v7, v8, v9
	v_cvt_pk_bf16_f32 v8, v26, v27
	v_cvt_pk_bf16_f32 v9, v10, v11
	global_store_dwordx4 v[22:23], v[2:5], off nt
	global_store_dwordx4 v[22:23], v[6:9], off offset:16 nt
	s_cbranch_scc1 .LBB0_728
